# th5 plus the K-loop closing barrier skipped on each unit's exit iteration: the leading half starts its epilogue one interval earlier beside the trailing half's last MFMA segment (no ALIGN idle)
# baseline (speedup 1.0000x reference)
.LBB0_256:
	s_add_u32 s22, s2, 0xfff80800
	s_addc_u32 s23, s3, -1
	s_add_i32 s48, 0, 0x10000
	s_cmp_eq_u32 s35, 28
	s_cselect_b32 s27, s8, s23
	s_cselect_b32 s26, s9, s22
	s_cselect_b32 s23, s15, s34
	s_cselect_b32 s22, s17, s33
	s_add_i32 s50, 0, 0x14000
	v_add_u32_e32 v176, s48, v191
	v_add_u32_e32 v188, s50, v191
	ds_read_b128 v[148:151], v176
	ds_read_b128 v[152:155], v176 offset:1024
	ds_read_b128 v[172:175], v176 offset:2048
	ds_read_b128 v[176:179], v176 offset:3072
	ds_read_b128 v[180:183], v188
	ds_read_b128 v[184:187], v188 offset:1024
	ds_read_b128 v[196:199], v188 offset:2048
	ds_read_b128 v[200:203], v188 offset:3072
	s_add_i32 m0, s39, 0xc000
	ds_read_b128 v[204:207], v194
	ds_read_b128 v[212:215], v194 offset:1024
	ds_read_b128 v[216:219], v194 offset:2048
	ds_read_b128 v[220:223], v194 offset:3072
	ds_read_b128 v[224:227], v194 offset:4096
	ds_read_b128 v[228:231], v194 offset:5120
	ds_read_b128 v[232:235], v194 offset:6144
	ds_read_b128 v[236:239], v194 offset:7168
	global_load_lds_dwordx4 v168, s[2:3]
	s_add_i32 m0, s39, 0xe000
	s_nop 0
	global_load_lds_dwordx4 v170, s[2:3]
	s_waitcnt vmcnt(8)
	s_waitcnt lgkmcnt(0)
	s_setprio 1
	s_barrier
	v_mfma_f32_16x16x32_bf16 v[144:147], v[148:151], v[204:207], v[144:147]
	v_mfma_f32_16x16x32_bf16 v[136:139], v[172:175], v[204:207], v[136:139]
	v_mfma_f32_16x16x32_bf16 v[128:131], v[148:151], v[216:219], v[128:131]
	v_mfma_f32_16x16x32_bf16 v[120:123], v[172:175], v[216:219], v[120:123]
	v_mfma_f32_16x16x32_bf16 v[112:115], v[148:151], v[224:227], v[112:115]
	v_mfma_f32_16x16x32_bf16 v[104:107], v[172:175], v[224:227], v[104:107]
	v_mfma_f32_16x16x32_bf16 v[96:99], v[148:151], v[232:235], v[96:99]
	v_mfma_f32_16x16x32_bf16 v[88:91], v[172:175], v[232:235], v[88:91]
	v_mfma_f32_16x16x32_bf16 v[144:147], v[152:155], v[212:215], v[144:147]
	v_mfma_f32_16x16x32_bf16 v[136:139], v[176:179], v[212:215], v[136:139]
	v_mfma_f32_16x16x32_bf16 v[128:131], v[152:155], v[220:223], v[128:131]
	v_mfma_f32_16x16x32_bf16 v[120:123], v[176:179], v[220:223], v[120:123]
	v_mfma_f32_16x16x32_bf16 v[112:115], v[152:155], v[228:231], v[112:115]
	v_mfma_f32_16x16x32_bf16 v[104:107], v[176:179], v[228:231], v[104:107]
	v_mfma_f32_16x16x32_bf16 v[96:99], v[152:155], v[236:239], v[96:99]
	v_mfma_f32_16x16x32_bf16 v[88:91], v[176:179], v[236:239], v[88:91]
	v_mfma_f32_16x16x32_bf16 v[140:143], v[180:183], v[204:207], v[140:143]
	v_mfma_f32_16x16x32_bf16 v[132:135], v[196:199], v[204:207], v[132:135]
	v_mfma_f32_16x16x32_bf16 v[124:127], v[180:183], v[216:219], v[124:127]
	v_mfma_f32_16x16x32_bf16 v[116:119], v[196:199], v[216:219], v[116:119]
	v_mfma_f32_16x16x32_bf16 v[108:111], v[180:183], v[224:227], v[108:111]
	v_mfma_f32_16x16x32_bf16 v[100:103], v[196:199], v[224:227], v[100:103]
	v_mfma_f32_16x16x32_bf16 v[92:95], v[180:183], v[232:235], v[92:95]
	v_mfma_f32_16x16x32_bf16 v[84:87], v[196:199], v[232:235], v[84:87]
	v_mfma_f32_16x16x32_bf16 v[140:143], v[184:187], v[212:215], v[140:143]
	v_mfma_f32_16x16x32_bf16 v[132:135], v[200:203], v[212:215], v[132:135]
	v_mfma_f32_16x16x32_bf16 v[124:127], v[184:187], v[220:223], v[124:127]
	v_mfma_f32_16x16x32_bf16 v[116:119], v[200:203], v[220:223], v[116:119]
	v_mfma_f32_16x16x32_bf16 v[108:111], v[184:187], v[228:231], v[108:111]
	v_mfma_f32_16x16x32_bf16 v[100:103], v[200:203], v[228:231], v[100:103]
	v_mfma_f32_16x16x32_bf16 v[92:95], v[184:187], v[236:239], v[92:95]
	v_mfma_f32_16x16x32_bf16 v[84:87], v[200:203], v[236:239], v[84:87]
	s_barrier
	s_setprio 0
	s_add_i32 s48, s48, s28
	s_add_u32 s98, s22, 0x80
	s_addc_u32 s99, s23, 0
	s_add_u32 s100, s26, 0x800
	s_addc_u32 s101, s27, 0
	s_mov_b32 m0, s48
	ds_read_b128 v[204:207], v194 offset:16384
	ds_read_b128 v[212:215], v194 offset:17408
	ds_read_b128 v[216:219], v194 offset:18432
	ds_read_b128 v[220:223], v194 offset:19456
	ds_read_b128 v[224:227], v194 offset:20480
	ds_read_b128 v[228:231], v194 offset:21504
	ds_read_b128 v[232:235], v194 offset:22528
	ds_read_b128 v[236:239], v194 offset:23552
	global_load_lds_dwordx4 v2, s[22:23]
	s_add_i32 m0, s48, 0x2000
	s_add_u32 s48, s22, 0x80000
	s_addc_u32 s49, s23, 0
	s_add_i32 s50, s50, s28
	global_load_lds_dwordx4 v156, s[22:23]
	s_mov_b32 m0, s50
	s_nop 0
	global_load_lds_dwordx4 v2, s[48:49]
	s_add_i32 m0, s50, 0x2000
	s_nop 0
	global_load_lds_dwordx4 v156, s[48:49]
	s_mov_b32 m0, s39
	s_nop 0
	global_load_lds_dwordx4 v160, s[26:27]
	s_mov_b32 m0, s41
	s_nop 0
	global_load_lds_dwordx4 v158, s[26:27]
	s_waitcnt vmcnt(8)
	s_waitcnt lgkmcnt(0)
	s_setprio 1
	s_barrier
	v_mfma_f32_16x16x32_bf16 v[80:83], v[148:151], v[204:207], v[80:83]
	v_mfma_f32_16x16x32_bf16 v[72:75], v[172:175], v[204:207], v[72:75]
	v_mfma_f32_16x16x32_bf16 v[64:67], v[148:151], v[216:219], v[64:67]
	v_mfma_f32_16x16x32_bf16 v[56:59], v[172:175], v[216:219], v[56:59]
	v_mfma_f32_16x16x32_bf16 v[48:51], v[148:151], v[224:227], v[48:51]
	v_mfma_f32_16x16x32_bf16 v[40:43], v[172:175], v[224:227], v[40:43]
	v_mfma_f32_16x16x32_bf16 v[32:35], v[148:151], v[232:235], v[32:35]
	v_mfma_f32_16x16x32_bf16 v[24:27], v[172:175], v[232:235], v[24:27]
	v_mfma_f32_16x16x32_bf16 v[80:83], v[152:155], v[212:215], v[80:83]
	v_mfma_f32_16x16x32_bf16 v[72:75], v[176:179], v[212:215], v[72:75]
	v_mfma_f32_16x16x32_bf16 v[64:67], v[152:155], v[220:223], v[64:67]
	v_mfma_f32_16x16x32_bf16 v[56:59], v[176:179], v[220:223], v[56:59]
	v_mfma_f32_16x16x32_bf16 v[48:51], v[152:155], v[228:231], v[48:51]
	v_mfma_f32_16x16x32_bf16 v[40:43], v[176:179], v[228:231], v[40:43]
	v_mfma_f32_16x16x32_bf16 v[32:35], v[152:155], v[236:239], v[32:35]
	v_mfma_f32_16x16x32_bf16 v[24:27], v[176:179], v[236:239], v[24:27]
	v_mfma_f32_16x16x32_bf16 v[76:79], v[180:183], v[204:207], v[76:79]
	v_mfma_f32_16x16x32_bf16 v[68:71], v[196:199], v[204:207], v[68:71]
	v_mfma_f32_16x16x32_bf16 v[60:63], v[180:183], v[216:219], v[60:63]
	v_mfma_f32_16x16x32_bf16 v[52:55], v[196:199], v[216:219], v[52:55]
	v_mfma_f32_16x16x32_bf16 v[44:47], v[180:183], v[224:227], v[44:47]
	v_mfma_f32_16x16x32_bf16 v[36:39], v[196:199], v[224:227], v[36:39]
	v_mfma_f32_16x16x32_bf16 v[28:31], v[180:183], v[232:235], v[28:31]
	v_mfma_f32_16x16x32_bf16 v[20:23], v[196:199], v[232:235], v[20:23]
	v_mfma_f32_16x16x32_bf16 v[76:79], v[184:187], v[212:215], v[76:79]
	v_mfma_f32_16x16x32_bf16 v[68:71], v[200:203], v[212:215], v[68:71]
	v_mfma_f32_16x16x32_bf16 v[60:63], v[184:187], v[220:223], v[60:63]
	v_mfma_f32_16x16x32_bf16 v[52:55], v[200:203], v[220:223], v[52:55]
	v_mfma_f32_16x16x32_bf16 v[44:47], v[184:187], v[228:231], v[44:47]
	v_mfma_f32_16x16x32_bf16 v[36:39], v[200:203], v[228:231], v[36:39]
	v_mfma_f32_16x16x32_bf16 v[28:31], v[184:187], v[236:239], v[28:31]
	v_mfma_f32_16x16x32_bf16 v[20:23], v[200:203], v[236:239], v[20:23]
	s_barrier
	s_setprio 0
	s_add_i32 s48, 0, 0x18000
	s_add_i32 s49, 0, 0x1c000
	v_add_u32_e32 v176, s48, v191
	v_add_u32_e32 v195, s49, v191
	ds_read_b128 v[148:151], v176
	ds_read_b128 v[152:155], v176 offset:1024
	ds_read_b128 v[172:175], v176 offset:2048
	ds_read_b128 v[176:179], v176 offset:3072
	ds_read_b128 v[180:183], v195
	ds_read_b128 v[184:187], v195 offset:1024
	ds_read_b128 v[196:199], v195 offset:2048
	ds_read_b128 v[200:203], v195 offset:3072
	s_add_u32 s26, s26, 0x80000
	s_addc_u32 s27, s27, 0
	s_mov_b32 m0, s42
	ds_read_b128 v[204:207], v194 offset:32768
	ds_read_b128 v[212:215], v194 offset:33792
	ds_read_b128 v[216:219], v194 offset:34816
	ds_read_b128 v[220:223], v194 offset:35840
	ds_read_b128 v[224:227], v194 offset:36864
	ds_read_b128 v[228:231], v194 offset:37888
	ds_read_b128 v[232:235], v194 offset:38912
	ds_read_b128 v[236:239], v194 offset:39936
	global_load_lds_dwordx4 v160, s[26:27]
	s_mov_b32 m0, s43
	s_nop 0
	global_load_lds_dwordx4 v158, s[26:27]
	s_waitcnt vmcnt(8)
	s_waitcnt lgkmcnt(0)
	s_setprio 1
	s_barrier
	v_mfma_f32_16x16x32_bf16 v[144:147], v[148:151], v[204:207], v[144:147]
	v_mfma_f32_16x16x32_bf16 v[136:139], v[172:175], v[204:207], v[136:139]
	v_mfma_f32_16x16x32_bf16 v[128:131], v[148:151], v[216:219], v[128:131]
	v_mfma_f32_16x16x32_bf16 v[120:123], v[172:175], v[216:219], v[120:123]
	v_mfma_f32_16x16x32_bf16 v[112:115], v[148:151], v[224:227], v[112:115]
	v_mfma_f32_16x16x32_bf16 v[104:107], v[172:175], v[224:227], v[104:107]
	v_mfma_f32_16x16x32_bf16 v[96:99], v[148:151], v[232:235], v[96:99]
	v_mfma_f32_16x16x32_bf16 v[88:91], v[172:175], v[232:235], v[88:91]
	v_mfma_f32_16x16x32_bf16 v[144:147], v[152:155], v[212:215], v[144:147]
	v_mfma_f32_16x16x32_bf16 v[136:139], v[176:179], v[212:215], v[136:139]
	v_mfma_f32_16x16x32_bf16 v[128:131], v[152:155], v[220:223], v[128:131]
	v_mfma_f32_16x16x32_bf16 v[120:123], v[176:179], v[220:223], v[120:123]
	v_mfma_f32_16x16x32_bf16 v[112:115], v[152:155], v[228:231], v[112:115]
	v_mfma_f32_16x16x32_bf16 v[104:107], v[176:179], v[228:231], v[104:107]
	v_mfma_f32_16x16x32_bf16 v[96:99], v[152:155], v[236:239], v[96:99]
	v_mfma_f32_16x16x32_bf16 v[88:91], v[176:179], v[236:239], v[88:91]
	v_mfma_f32_16x16x32_bf16 v[140:143], v[180:183], v[204:207], v[140:143]
	v_mfma_f32_16x16x32_bf16 v[132:135], v[196:199], v[204:207], v[132:135]
	v_mfma_f32_16x16x32_bf16 v[124:127], v[180:183], v[216:219], v[124:127]
	v_mfma_f32_16x16x32_bf16 v[116:119], v[196:199], v[216:219], v[116:119]
	v_mfma_f32_16x16x32_bf16 v[108:111], v[180:183], v[224:227], v[108:111]
	v_mfma_f32_16x16x32_bf16 v[100:103], v[196:199], v[224:227], v[100:103]
	v_mfma_f32_16x16x32_bf16 v[92:95], v[180:183], v[232:235], v[92:95]
	v_mfma_f32_16x16x32_bf16 v[84:87], v[196:199], v[232:235], v[84:87]
	v_mfma_f32_16x16x32_bf16 v[140:143], v[184:187], v[212:215], v[140:143]
	v_mfma_f32_16x16x32_bf16 v[132:135], v[200:203], v[212:215], v[132:135]
	v_mfma_f32_16x16x32_bf16 v[124:127], v[184:187], v[220:223], v[124:127]
	v_mfma_f32_16x16x32_bf16 v[116:119], v[200:203], v[220:223], v[116:119]
	v_mfma_f32_16x16x32_bf16 v[108:111], v[184:187], v[228:231], v[108:111]
	v_mfma_f32_16x16x32_bf16 v[100:103], v[200:203], v[228:231], v[100:103]
	v_mfma_f32_16x16x32_bf16 v[92:95], v[184:187], v[236:239], v[92:95]
	v_mfma_f32_16x16x32_bf16 v[84:87], v[200:203], v[236:239], v[84:87]
	s_barrier
	s_setprio 0
	s_add_i32 s26, s48, s28
	s_mov_b32 m0, s26
	ds_read_b128 v[204:207], v194 offset:49152
	ds_read_b128 v[212:215], v194 offset:50176
	ds_read_b128 v[216:219], v194 offset:51200
	ds_read_b128 v[220:223], v194 offset:52224
	ds_read_b128 v[224:227], v194 offset:53248
	ds_read_b128 v[228:231], v194 offset:54272
	ds_read_b128 v[232:235], v194 offset:55296
	ds_read_b128 v[236:239], v194 offset:56320
	global_load_lds_dwordx4 v2, s[98:99]
	s_add_i32 m0, s26, 0x2000
	s_add_u32 s22, s22, 0x80080
	s_addc_u32 s23, s23, 0
	s_add_i32 s26, s49, s28
	global_load_lds_dwordx4 v156, s[98:99]
	s_mov_b32 m0, s26
	s_nop 0
	global_load_lds_dwordx4 v2, s[22:23]
	s_add_i32 m0, s26, 0x2000
	s_nop 0
	global_load_lds_dwordx4 v156, s[22:23]
	s_mov_b32 m0, s44
	s_nop 0
	global_load_lds_dwordx4 v160, s[100:101]
	s_mov_b32 m0, s45
	s_nop 0
	global_load_lds_dwordx4 v158, s[100:101]
	s_waitcnt vmcnt(8)
	s_waitcnt lgkmcnt(0)
	s_setprio 1
	s_barrier
	v_mfma_f32_16x16x32_bf16 v[80:83], v[148:151], v[204:207], v[80:83]
	v_mfma_f32_16x16x32_bf16 v[72:75], v[172:175], v[204:207], v[72:75]
	v_mfma_f32_16x16x32_bf16 v[64:67], v[148:151], v[216:219], v[64:67]
	v_mfma_f32_16x16x32_bf16 v[56:59], v[172:175], v[216:219], v[56:59]
	v_mfma_f32_16x16x32_bf16 v[48:51], v[148:151], v[224:227], v[48:51]
	v_mfma_f32_16x16x32_bf16 v[40:43], v[172:175], v[224:227], v[40:43]
	v_mfma_f32_16x16x32_bf16 v[32:35], v[148:151], v[232:235], v[32:35]
	v_mfma_f32_16x16x32_bf16 v[24:27], v[172:175], v[232:235], v[24:27]
	v_mfma_f32_16x16x32_bf16 v[80:83], v[152:155], v[212:215], v[80:83]
	v_mfma_f32_16x16x32_bf16 v[72:75], v[176:179], v[212:215], v[72:75]
	v_mfma_f32_16x16x32_bf16 v[64:67], v[152:155], v[220:223], v[64:67]
	v_mfma_f32_16x16x32_bf16 v[56:59], v[176:179], v[220:223], v[56:59]
	v_mfma_f32_16x16x32_bf16 v[48:51], v[152:155], v[228:231], v[48:51]
	v_mfma_f32_16x16x32_bf16 v[40:43], v[176:179], v[228:231], v[40:43]
	v_mfma_f32_16x16x32_bf16 v[32:35], v[152:155], v[236:239], v[32:35]
	v_mfma_f32_16x16x32_bf16 v[24:27], v[176:179], v[236:239], v[24:27]
	v_mfma_f32_16x16x32_bf16 v[76:79], v[180:183], v[204:207], v[76:79]
	v_mfma_f32_16x16x32_bf16 v[68:71], v[196:199], v[204:207], v[68:71]
	v_mfma_f32_16x16x32_bf16 v[60:63], v[180:183], v[216:219], v[60:63]
	v_mfma_f32_16x16x32_bf16 v[52:55], v[196:199], v[216:219], v[52:55]
	v_mfma_f32_16x16x32_bf16 v[44:47], v[180:183], v[224:227], v[44:47]
	v_mfma_f32_16x16x32_bf16 v[36:39], v[196:199], v[224:227], v[36:39]
	v_mfma_f32_16x16x32_bf16 v[28:31], v[180:183], v[232:235], v[28:31]
	v_mfma_f32_16x16x32_bf16 v[20:23], v[196:199], v[232:235], v[20:23]
	v_mfma_f32_16x16x32_bf16 v[76:79], v[184:187], v[212:215], v[76:79]
	v_mfma_f32_16x16x32_bf16 v[68:71], v[200:203], v[212:215], v[68:71]
	v_mfma_f32_16x16x32_bf16 v[60:63], v[184:187], v[220:223], v[60:63]
	v_mfma_f32_16x16x32_bf16 v[52:55], v[200:203], v[220:223], v[52:55]
	s_cmp_eq_u32 s35, 28
	v_mfma_f32_16x16x32_bf16 v[44:47], v[184:187], v[228:231], v[44:47]
	v_mfma_f32_16x16x32_bf16 v[36:39], v[200:203], v[228:231], v[36:39]
	v_mfma_f32_16x16x32_bf16 v[28:31], v[184:187], v[236:239], v[28:31]
	v_mfma_f32_16x16x32_bf16 v[20:23], v[200:203], v[236:239], v[20:23]
	s_cbranch_scc1 .Lexit_256
	s_barrier
	s_setprio 0
	s_add_i32 s35, s35, 2
	s_add_u32 s2, s2, 0x1000
	s_addc_u32 s3, s3, 0
	s_add_u32 s33, s33, 0x100
	s_addc_u32 s34, s34, 0
	s_cmp_gt_u32 s35, 29
	s_cbranch_scc0 .LBB0_256
.Lexit_256:
	s_setprio 0
	s_add_i32 s35, s35, 2
	s_add_u32 s2, s2, 0x1000
	s_addc_u32 s3, s3, 0
	s_add_u32 s33, s33, 0x100
	s_addc_u32 s34, s34, 0

.LBB0_489:
	s_add_u32 s26, s22, 0xfff80800
	s_addc_u32 s27, s23, -1
	s_add_i32 s34, 0, 0x10000
	s_cmp_eq_u32 s33, 28
	s_cselect_b32 s39, s3, s27
	s_cselect_b32 s38, s6, s26
	s_cselect_b32 s27, s8, s17
	s_cselect_b32 s26, s9, s15
	s_add_i32 s53, 0, 0x14000
	v_add_u32_e32 v144, s34, v168
	v_add_u32_e32 v160, s53, v168
	ds_read_b128 v[4:7], v144
	ds_read_b128 v[8:11], v144 offset:1024
	ds_read_b128 v[140:143], v144 offset:2048
	ds_read_b128 v[144:147], v144 offset:3072
	ds_read_b128 v[172:175], v160
	ds_read_b128 v[176:179], v160 offset:1024
	ds_read_b128 v[180:183], v160 offset:2048
	ds_read_b128 v[184:187], v160 offset:3072
	s_add_i32 m0, s13, 0xc000
	ds_read_b128 v[188:191], v170
	ds_read_b128 v[192:195], v170 offset:1024
	ds_read_b128 v[196:199], v170 offset:2048
	ds_read_b128 v[200:203], v170 offset:3072
	ds_read_b128 v[204:207], v170 offset:4096
	ds_read_b128 v[212:215], v170 offset:5120
	ds_read_b128 v[216:219], v170 offset:6144
	ds_read_b128 v[220:223], v170 offset:7168
	global_load_lds_dwordx4 v156, s[22:23]
	s_add_i32 m0, s13, 0xe000
	s_nop 0
	global_load_lds_dwordx4 v158, s[22:23]
	s_waitcnt vmcnt(8)
	s_waitcnt lgkmcnt(0)
	s_setprio 1
	s_barrier
	v_mfma_f32_16x16x32_bf16 v[136:139], v[4:7], v[188:191], v[136:139]
	v_mfma_f32_16x16x32_bf16 v[132:135], v[140:143], v[188:191], v[132:135]
	v_mfma_f32_16x16x32_bf16 v[128:131], v[4:7], v[196:199], v[128:131]
	v_mfma_f32_16x16x32_bf16 v[120:123], v[140:143], v[196:199], v[120:123]
	v_mfma_f32_16x16x32_bf16 v[112:115], v[4:7], v[204:207], v[112:115]
	v_mfma_f32_16x16x32_bf16 v[104:107], v[140:143], v[204:207], v[104:107]
	v_mfma_f32_16x16x32_bf16 v[96:99], v[4:7], v[216:219], v[96:99]
	v_mfma_f32_16x16x32_bf16 v[88:91], v[140:143], v[216:219], v[88:91]
	v_mfma_f32_16x16x32_bf16 v[136:139], v[8:11], v[192:195], v[136:139]
	v_mfma_f32_16x16x32_bf16 v[132:135], v[144:147], v[192:195], v[132:135]
	v_mfma_f32_16x16x32_bf16 v[128:131], v[8:11], v[200:203], v[128:131]
	v_mfma_f32_16x16x32_bf16 v[120:123], v[144:147], v[200:203], v[120:123]
	v_mfma_f32_16x16x32_bf16 v[112:115], v[8:11], v[212:215], v[112:115]
	v_mfma_f32_16x16x32_bf16 v[104:107], v[144:147], v[212:215], v[104:107]
	v_mfma_f32_16x16x32_bf16 v[96:99], v[8:11], v[220:223], v[96:99]
	v_mfma_f32_16x16x32_bf16 v[88:91], v[144:147], v[220:223], v[88:91]
	v_mfma_f32_16x16x32_bf16 v[124:127], v[172:175], v[188:191], v[124:127]
	v_mfma_f32_16x16x32_bf16 v[116:119], v[180:183], v[188:191], v[116:119]
	v_mfma_f32_16x16x32_bf16 v[108:111], v[172:175], v[196:199], v[108:111]
	v_mfma_f32_16x16x32_bf16 v[100:103], v[180:183], v[196:199], v[100:103]
	v_mfma_f32_16x16x32_bf16 v[92:95], v[172:175], v[204:207], v[92:95]
	v_mfma_f32_16x16x32_bf16 v[84:87], v[180:183], v[204:207], v[84:87]
	v_mfma_f32_16x16x32_bf16 v[80:83], v[172:175], v[216:219], v[80:83]
	v_mfma_f32_16x16x32_bf16 v[76:79], v[180:183], v[216:219], v[76:79]
	v_mfma_f32_16x16x32_bf16 v[124:127], v[176:179], v[192:195], v[124:127]
	v_mfma_f32_16x16x32_bf16 v[116:119], v[184:187], v[192:195], v[116:119]
	v_mfma_f32_16x16x32_bf16 v[108:111], v[176:179], v[200:203], v[108:111]
	v_mfma_f32_16x16x32_bf16 v[100:103], v[184:187], v[200:203], v[100:103]
	v_mfma_f32_16x16x32_bf16 v[92:95], v[176:179], v[212:215], v[92:95]
	v_mfma_f32_16x16x32_bf16 v[84:87], v[184:187], v[212:215], v[84:87]
	v_mfma_f32_16x16x32_bf16 v[80:83], v[176:179], v[220:223], v[80:83]
	v_mfma_f32_16x16x32_bf16 v[76:79], v[184:187], v[220:223], v[76:79]
	s_barrier
	s_setprio 0
	s_add_i32 s34, s34, s7
	s_add_u32 s98, s26, 0x80
	s_addc_u32 s99, s27, 0
	s_add_u32 s100, s38, 0x800
	s_addc_u32 s101, s39, 0
	s_mov_b32 m0, s34
	ds_read_b128 v[188:191], v170 offset:16384
	ds_read_b128 v[192:195], v170 offset:17408
	ds_read_b128 v[196:199], v170 offset:18432
	ds_read_b128 v[200:203], v170 offset:19456
	ds_read_b128 v[204:207], v170 offset:20480
	ds_read_b128 v[212:215], v170 offset:21504
	ds_read_b128 v[216:219], v170 offset:22528
	ds_read_b128 v[220:223], v170 offset:23552
	global_load_lds_dwordx4 v2, s[26:27]
	s_add_i32 m0, s34, 0x2000
	s_add_u32 s34, s26, 0x80000
	s_addc_u32 s35, s27, 0
	s_add_i32 s53, s53, s7
	global_load_lds_dwordx4 v148, s[26:27]
	s_mov_b32 m0, s53
	s_nop 0
	global_load_lds_dwordx4 v2, s[34:35]
	s_add_i32 m0, s53, 0x2000
	s_nop 0
	global_load_lds_dwordx4 v148, s[34:35]
	s_mov_b32 m0, s13
	s_nop 0
	global_load_lds_dwordx4 v152, s[38:39]
	s_mov_b32 m0, s46
	s_nop 0
	global_load_lds_dwordx4 v150, s[38:39]
	s_waitcnt vmcnt(8)
	s_waitcnt lgkmcnt(0)
	s_setprio 1
	s_barrier
	v_mfma_f32_16x16x32_bf16 v[72:75], v[4:7], v[188:191], v[72:75]
	v_mfma_f32_16x16x32_bf16 v[68:71], v[140:143], v[188:191], v[68:71]
	v_mfma_f32_16x16x32_bf16 v[64:67], v[4:7], v[196:199], v[64:67]
	v_mfma_f32_16x16x32_bf16 v[56:59], v[140:143], v[196:199], v[56:59]
	v_mfma_f32_16x16x32_bf16 v[48:51], v[4:7], v[204:207], v[48:51]
	v_mfma_f32_16x16x32_bf16 v[40:43], v[140:143], v[204:207], v[40:43]
	v_mfma_f32_16x16x32_bf16 v[4:7], v[4:7], v[216:219], v[32:35]
	v_mfma_f32_16x16x32_bf16 v[72:75], v[8:11], v[192:195], v[72:75]
	v_mfma_f32_16x16x32_bf16 v[68:71], v[144:147], v[192:195], v[68:71]
	v_mfma_f32_16x16x32_bf16 v[64:67], v[8:11], v[200:203], v[64:67]
	v_mfma_f32_16x16x32_bf16 v[56:59], v[144:147], v[200:203], v[56:59]
	v_mfma_f32_16x16x32_bf16 v[48:51], v[8:11], v[212:215], v[48:51]
	v_mfma_f32_16x16x32_bf16 v[40:43], v[144:147], v[212:215], v[40:43]
	v_mfma_f32_16x16x32_bf16 v[4:7], v[8:11], v[220:223], v[4:7]
	v_mfma_f32_16x16x32_bf16 v[8:11], v[140:143], v[216:219], v[24:27]
	v_mfma_f32_16x16x32_bf16 v[8:11], v[144:147], v[220:223], v[8:11]
	v_mfma_f32_16x16x32_bf16 v[24:27], v[172:175], v[188:191], v[60:63]
	v_mfma_f32_16x16x32_bf16 v[60:63], v[176:179], v[192:195], v[24:27]
	v_mfma_f32_16x16x32_bf16 v[24:27], v[180:183], v[188:191], v[52:55]
	v_mfma_f32_16x16x32_bf16 v[52:55], v[184:187], v[192:195], v[24:27]
	v_mfma_f32_16x16x32_bf16 v[24:27], v[172:175], v[196:199], v[44:47]
	v_mfma_f32_16x16x32_bf16 v[44:47], v[176:179], v[200:203], v[24:27]
	v_mfma_f32_16x16x32_bf16 v[24:27], v[180:183], v[196:199], v[36:39]
	v_mfma_f32_16x16x32_bf16 v[36:39], v[184:187], v[200:203], v[24:27]
	v_mfma_f32_16x16x32_bf16 v[24:27], v[172:175], v[204:207], v[28:31]
	v_mfma_f32_16x16x32_bf16 v[20:23], v[180:183], v[204:207], v[20:23]
	v_mfma_f32_16x16x32_bf16 v[16:19], v[172:175], v[216:219], v[16:19]
	v_mfma_f32_16x16x32_bf16 v[12:15], v[180:183], v[216:219], v[12:15]
	v_mfma_f32_16x16x32_bf16 v[28:31], v[176:179], v[212:215], v[24:27]
	v_mfma_f32_16x16x32_bf16 v[20:23], v[184:187], v[212:215], v[20:23]
	v_mfma_f32_16x16x32_bf16 v[16:19], v[176:179], v[220:223], v[16:19]
	v_mfma_f32_16x16x32_bf16 v[12:15], v[184:187], v[220:223], v[12:15]
	s_barrier
	s_setprio 0
	s_add_i32 s53, 0, 0x18000
	s_add_i32 s54, 0, 0x1c000
	v_add_u32_e32 v144, s53, v168
	v_add_u32_e32 v171, s54, v168
	ds_read_b128 v[24:27], v144
	ds_read_b128 v[32:35], v144 offset:1024
	ds_read_b128 v[140:143], v144 offset:2048
	ds_read_b128 v[144:147], v144 offset:3072
	ds_read_b128 v[172:175], v171
	ds_read_b128 v[176:179], v171 offset:1024
	ds_read_b128 v[180:183], v171 offset:2048
	ds_read_b128 v[184:187], v171 offset:3072
	s_add_u32 s34, s38, 0x80000
	s_addc_u32 s35, s39, 0
	s_mov_b32 m0, s47
	ds_read_b128 v[188:191], v170 offset:32768
	ds_read_b128 v[192:195], v170 offset:33792
	ds_read_b128 v[196:199], v170 offset:34816
	ds_read_b128 v[200:203], v170 offset:35840
	ds_read_b128 v[204:207], v170 offset:36864
	ds_read_b128 v[212:215], v170 offset:37888
	ds_read_b128 v[216:219], v170 offset:38912
	ds_read_b128 v[220:223], v170 offset:39936
	global_load_lds_dwordx4 v152, s[34:35]
	s_mov_b32 m0, s48
	s_nop 0
	global_load_lds_dwordx4 v150, s[34:35]
	s_waitcnt vmcnt(8)
	s_waitcnt lgkmcnt(0)
	s_setprio 1
	s_barrier
	v_mfma_f32_16x16x32_bf16 v[136:139], v[24:27], v[188:191], v[136:139]
	v_mfma_f32_16x16x32_bf16 v[132:135], v[140:143], v[188:191], v[132:135]
	v_mfma_f32_16x16x32_bf16 v[128:131], v[24:27], v[196:199], v[128:131]
	v_mfma_f32_16x16x32_bf16 v[120:123], v[140:143], v[196:199], v[120:123]
	v_mfma_f32_16x16x32_bf16 v[112:115], v[24:27], v[204:207], v[112:115]
	v_mfma_f32_16x16x32_bf16 v[104:107], v[140:143], v[204:207], v[104:107]
	v_mfma_f32_16x16x32_bf16 v[96:99], v[24:27], v[216:219], v[96:99]
	v_mfma_f32_16x16x32_bf16 v[88:91], v[140:143], v[216:219], v[88:91]
	v_mfma_f32_16x16x32_bf16 v[136:139], v[32:35], v[192:195], v[136:139]
	v_mfma_f32_16x16x32_bf16 v[132:135], v[144:147], v[192:195], v[132:135]
	v_mfma_f32_16x16x32_bf16 v[128:131], v[32:35], v[200:203], v[128:131]
	v_mfma_f32_16x16x32_bf16 v[120:123], v[144:147], v[200:203], v[120:123]
	v_mfma_f32_16x16x32_bf16 v[112:115], v[32:35], v[212:215], v[112:115]
	v_mfma_f32_16x16x32_bf16 v[104:107], v[144:147], v[212:215], v[104:107]
	v_mfma_f32_16x16x32_bf16 v[96:99], v[32:35], v[220:223], v[96:99]
	v_mfma_f32_16x16x32_bf16 v[88:91], v[144:147], v[220:223], v[88:91]
	v_mfma_f32_16x16x32_bf16 v[124:127], v[172:175], v[188:191], v[124:127]
	v_mfma_f32_16x16x32_bf16 v[116:119], v[180:183], v[188:191], v[116:119]
	v_mfma_f32_16x16x32_bf16 v[108:111], v[172:175], v[196:199], v[108:111]
	v_mfma_f32_16x16x32_bf16 v[100:103], v[180:183], v[196:199], v[100:103]
	v_mfma_f32_16x16x32_bf16 v[92:95], v[172:175], v[204:207], v[92:95]
	v_mfma_f32_16x16x32_bf16 v[84:87], v[180:183], v[204:207], v[84:87]
	v_mfma_f32_16x16x32_bf16 v[80:83], v[172:175], v[216:219], v[80:83]
	v_mfma_f32_16x16x32_bf16 v[76:79], v[180:183], v[216:219], v[76:79]
	v_mfma_f32_16x16x32_bf16 v[124:127], v[176:179], v[192:195], v[124:127]
	v_mfma_f32_16x16x32_bf16 v[116:119], v[184:187], v[192:195], v[116:119]
	v_mfma_f32_16x16x32_bf16 v[108:111], v[176:179], v[200:203], v[108:111]
	v_mfma_f32_16x16x32_bf16 v[100:103], v[184:187], v[200:203], v[100:103]
	v_mfma_f32_16x16x32_bf16 v[92:95], v[176:179], v[212:215], v[92:95]
	v_mfma_f32_16x16x32_bf16 v[84:87], v[184:187], v[212:215], v[84:87]
	v_mfma_f32_16x16x32_bf16 v[80:83], v[176:179], v[220:223], v[80:83]
	v_mfma_f32_16x16x32_bf16 v[76:79], v[184:187], v[220:223], v[76:79]
	s_barrier
	s_setprio 0
	s_add_i32 s34, s53, s7
	s_mov_b32 m0, s34
	ds_read_b128 v[188:191], v170 offset:49152
	ds_read_b128 v[192:195], v170 offset:50176
	ds_read_b128 v[196:199], v170 offset:51200
	ds_read_b128 v[200:203], v170 offset:52224
	ds_read_b128 v[204:207], v170 offset:53248
	ds_read_b128 v[212:215], v170 offset:54272
	ds_read_b128 v[216:219], v170 offset:55296
	ds_read_b128 v[220:223], v170 offset:56320
	global_load_lds_dwordx4 v2, s[98:99]
	s_add_i32 m0, s34, 0x2000
	s_add_u32 s26, s26, 0x80080
	s_addc_u32 s27, s27, 0
	s_add_i32 s34, s54, s7
	global_load_lds_dwordx4 v148, s[98:99]
	s_mov_b32 m0, s34
	s_nop 0
	global_load_lds_dwordx4 v2, s[26:27]
	s_add_i32 m0, s34, 0x2000
	s_nop 0
	global_load_lds_dwordx4 v148, s[26:27]
	s_mov_b32 m0, s49
	s_nop 0
	global_load_lds_dwordx4 v152, s[100:101]
	s_mov_b32 m0, s50
	s_nop 0
	global_load_lds_dwordx4 v150, s[100:101]
	s_waitcnt vmcnt(8)
	s_waitcnt lgkmcnt(0)
	s_setprio 1
	s_barrier
	v_mfma_f32_16x16x32_bf16 v[72:75], v[24:27], v[188:191], v[72:75]
	v_mfma_f32_16x16x32_bf16 v[64:67], v[24:27], v[196:199], v[64:67]
	v_mfma_f32_16x16x32_bf16 v[48:51], v[24:27], v[204:207], v[48:51]
	v_mfma_f32_16x16x32_bf16 v[4:7], v[24:27], v[216:219], v[4:7]
	v_mfma_f32_16x16x32_bf16 v[72:75], v[32:35], v[192:195], v[72:75]
	v_mfma_f32_16x16x32_bf16 v[68:71], v[140:143], v[188:191], v[68:71]
	v_mfma_f32_16x16x32_bf16 v[64:67], v[32:35], v[200:203], v[64:67]
	v_mfma_f32_16x16x32_bf16 v[56:59], v[140:143], v[196:199], v[56:59]
	v_mfma_f32_16x16x32_bf16 v[48:51], v[32:35], v[212:215], v[48:51]
	v_mfma_f32_16x16x32_bf16 v[40:43], v[140:143], v[204:207], v[40:43]
	v_mfma_f32_16x16x32_bf16 v[32:35], v[32:35], v[220:223], v[4:7]
	v_mfma_f32_16x16x32_bf16 v[4:7], v[140:143], v[216:219], v[8:11]
	v_mfma_f32_16x16x32_bf16 v[68:71], v[144:147], v[192:195], v[68:71]
	v_mfma_f32_16x16x32_bf16 v[56:59], v[144:147], v[200:203], v[56:59]
	v_mfma_f32_16x16x32_bf16 v[40:43], v[144:147], v[212:215], v[40:43]
	v_mfma_f32_16x16x32_bf16 v[24:27], v[144:147], v[220:223], v[4:7]
	v_mfma_f32_16x16x32_bf16 v[4:7], v[172:175], v[188:191], v[60:63]
	v_mfma_f32_16x16x32_bf16 v[60:63], v[176:179], v[192:195], v[4:7]
	v_mfma_f32_16x16x32_bf16 v[4:7], v[180:183], v[188:191], v[52:55]
	v_mfma_f32_16x16x32_bf16 v[52:55], v[184:187], v[192:195], v[4:7]
	v_mfma_f32_16x16x32_bf16 v[4:7], v[172:175], v[196:199], v[44:47]
	v_mfma_f32_16x16x32_bf16 v[44:47], v[176:179], v[200:203], v[4:7]
	v_mfma_f32_16x16x32_bf16 v[4:7], v[180:183], v[196:199], v[36:39]
	v_mfma_f32_16x16x32_bf16 v[36:39], v[184:187], v[200:203], v[4:7]
	v_mfma_f32_16x16x32_bf16 v[4:7], v[172:175], v[204:207], v[28:31]
	v_mfma_f32_16x16x32_bf16 v[28:31], v[176:179], v[212:215], v[4:7]
	v_mfma_f32_16x16x32_bf16 v[4:7], v[180:183], v[204:207], v[20:23]
	v_mfma_f32_16x16x32_bf16 v[20:23], v[184:187], v[212:215], v[4:7]
	s_cmp_eq_u32 s33, 28
	v_mfma_f32_16x16x32_bf16 v[4:7], v[172:175], v[216:219], v[16:19]
	v_mfma_f32_16x16x32_bf16 v[16:19], v[176:179], v[220:223], v[4:7]
	v_mfma_f32_16x16x32_bf16 v[4:7], v[180:183], v[216:219], v[12:15]
	v_mfma_f32_16x16x32_bf16 v[12:15], v[184:187], v[220:223], v[4:7]
	s_cbranch_scc1 .Lexit_489
	s_barrier
	s_setprio 0
	s_add_i32 s33, s33, 2
	s_add_u32 s22, s22, 0x1000
	s_addc_u32 s23, s23, 0
	s_add_u32 s15, s15, 0x100
	s_addc_u32 s17, s17, 0
	s_cmp_gt_u32 s33, 29
	s_cbranch_scc0 .LBB0_489
.Lexit_489:
	s_setprio 0
	s_add_i32 s33, s33, 2
	s_add_u32 s22, s22, 0x1000
	s_addc_u32 s23, s23, 0
	s_add_u32 s15, s15, 0x100
	s_addc_u32 s17, s17, 0

.LBB0_832:
	s_add_i32 s28, s9, 2
	s_add_u32 s22, s2, s100
	s_addc_u32 s23, s3, 0
	s_add_i32 s29, 0, 0x10000
	s_cmp_eq_u32 s52, s9
	s_cselect_b32 s23, s1, s23
	s_cselect_b32 s22, s0, s22
	v_add_u32_e32 v2, s29, v147
	s_cselect_b32 s35, s21, s8
	s_cselect_b32 s34, s20, s7
	s_add_i32 s9, 0, 0x14000
	ds_read_b128 v[152:155], v2
	ds_read_b128 v[156:159], v2 offset:1024
	ds_read_b128 v[160:163], v2 offset:2048
	ds_read_b128 v[168:171], v2 offset:3072
	v_add_u32_e32 v2, s9, v147
	ds_read_b128 v[172:175], v2
	ds_read_b128 v[176:179], v2 offset:1024
	ds_read_b128 v[180:183], v2 offset:2048
	ds_read_b128 v[184:187], v2 offset:3072
	s_add_i32 m0, s47, 0xc000
	ds_read_b128 v[188:191], v150
	ds_read_b128 v[192:195], v150 offset:1024
	ds_read_b128 v[196:199], v150 offset:2048
	ds_read_b128 v[200:203], v150 offset:3072
	ds_read_b128 v[204:207], v150 offset:4096
	ds_read_b128 v[210:213], v150 offset:5120
	ds_read_b128 v[214:217], v150 offset:6144
	ds_read_b128 v[218:221], v150 offset:7168
	global_load_lds_dwordx4 v140, s[2:3]
	s_add_i32 m0, s47, 0xe000
	s_nop 0
	global_load_lds_dwordx4 v142, s[2:3]
	s_waitcnt vmcnt(8)
	s_waitcnt lgkmcnt(0)
	s_setprio 1
	s_barrier
	v_mfma_f32_16x16x32_bf16 v[128:131], v[152:155], v[188:191], v[128:131]
	v_mfma_f32_16x16x32_bf16 v[124:127], v[160:163], v[188:191], v[124:127]
	v_mfma_f32_16x16x32_bf16 v[112:115], v[152:155], v[196:199], v[112:115]
	v_mfma_f32_16x16x32_bf16 v[108:111], v[160:163], v[196:199], v[108:111]
	v_mfma_f32_16x16x32_bf16 v[96:99], v[152:155], v[204:207], v[96:99]
	v_mfma_f32_16x16x32_bf16 v[92:95], v[160:163], v[204:207], v[92:95]
	v_mfma_f32_16x16x32_bf16 v[80:83], v[152:155], v[214:217], v[80:83]
	v_mfma_f32_16x16x32_bf16 v[76:79], v[160:163], v[214:217], v[76:79]
	v_mfma_f32_16x16x32_bf16 v[128:131], v[156:159], v[192:195], v[128:131]
	v_mfma_f32_16x16x32_bf16 v[124:127], v[168:171], v[192:195], v[124:127]
	v_mfma_f32_16x16x32_bf16 v[112:115], v[156:159], v[200:203], v[112:115]
	v_mfma_f32_16x16x32_bf16 v[108:111], v[168:171], v[200:203], v[108:111]
	v_mfma_f32_16x16x32_bf16 v[96:99], v[156:159], v[210:213], v[96:99]
	v_mfma_f32_16x16x32_bf16 v[92:95], v[168:171], v[210:213], v[92:95]
	v_mfma_f32_16x16x32_bf16 v[80:83], v[156:159], v[218:221], v[80:83]
	v_mfma_f32_16x16x32_bf16 v[76:79], v[168:171], v[218:221], v[76:79]
	v_mfma_f32_16x16x32_bf16 v[120:123], v[172:175], v[188:191], v[120:123]
	v_mfma_f32_16x16x32_bf16 v[116:119], v[180:183], v[188:191], v[116:119]
	v_mfma_f32_16x16x32_bf16 v[104:107], v[172:175], v[196:199], v[104:107]
	v_mfma_f32_16x16x32_bf16 v[100:103], v[180:183], v[196:199], v[100:103]
	v_mfma_f32_16x16x32_bf16 v[88:91], v[172:175], v[204:207], v[88:91]
	v_mfma_f32_16x16x32_bf16 v[84:87], v[180:183], v[204:207], v[84:87]
	v_mfma_f32_16x16x32_bf16 v[72:75], v[172:175], v[214:217], v[72:75]
	v_mfma_f32_16x16x32_bf16 v[68:71], v[180:183], v[214:217], v[68:71]
	v_mfma_f32_16x16x32_bf16 v[120:123], v[176:179], v[192:195], v[120:123]
	v_mfma_f32_16x16x32_bf16 v[116:119], v[184:187], v[192:195], v[116:119]
	v_mfma_f32_16x16x32_bf16 v[104:107], v[176:179], v[200:203], v[104:107]
	v_mfma_f32_16x16x32_bf16 v[100:103], v[184:187], v[200:203], v[100:103]
	v_mfma_f32_16x16x32_bf16 v[88:91], v[176:179], v[210:213], v[88:91]
	v_mfma_f32_16x16x32_bf16 v[84:87], v[184:187], v[210:213], v[84:87]
	v_mfma_f32_16x16x32_bf16 v[72:75], v[176:179], v[218:221], v[72:75]
	v_mfma_f32_16x16x32_bf16 v[68:71], v[184:187], v[218:221], v[68:71]
	s_barrier
	s_setprio 0
	s_add_i32 s29, s29, s26
	s_mov_b32 m0, s29
	ds_read_b128 v[188:191], v150 offset:16384
	ds_read_b128 v[192:195], v150 offset:17408
	ds_read_b128 v[196:199], v150 offset:18432
	ds_read_b128 v[200:203], v150 offset:19456
	ds_read_b128 v[204:207], v150 offset:20480
	ds_read_b128 v[210:213], v150 offset:21504
	ds_read_b128 v[214:217], v150 offset:22528
	ds_read_b128 v[218:221], v150 offset:23552
	global_load_lds_dwordx4 v136, s[34:35]
	s_add_i32 m0, s29, 0x2000
	s_add_i32 s9, s9, s26
	global_load_lds_dwordx4 v132, s[34:35]
	s_add_u32 s34, s34, s16
	s_addc_u32 s35, s35, 0
	s_mov_b32 m0, s9
	s_nop 0
	global_load_lds_dwordx4 v136, s[34:35]
	s_add_i32 m0, s9, 0x2000
	s_nop 0
	global_load_lds_dwordx4 v132, s[34:35]
	s_mov_b32 m0, s47
	s_nop 0
	global_load_lds_dwordx4 v138, s[22:23]
	s_mov_b32 m0, s48
	s_nop 0
	global_load_lds_dwordx4 v134, s[22:23]
	s_waitcnt vmcnt(8)
	s_waitcnt lgkmcnt(0)
	s_setprio 1
	s_barrier
	v_mfma_f32_16x16x32_bf16 v[64:67], v[152:155], v[188:191], v[64:67]
	v_mfma_f32_16x16x32_bf16 v[60:63], v[160:163], v[188:191], v[60:63]
	v_mfma_f32_16x16x32_bf16 v[48:51], v[152:155], v[196:199], v[48:51]
	v_mfma_f32_16x16x32_bf16 v[44:47], v[160:163], v[196:199], v[44:47]
	v_mfma_f32_16x16x32_bf16 v[32:35], v[152:155], v[204:207], v[32:35]
	v_mfma_f32_16x16x32_bf16 v[28:31], v[160:163], v[204:207], v[28:31]
	v_mfma_f32_16x16x32_bf16 v[16:19], v[152:155], v[214:217], v[16:19]
	v_mfma_f32_16x16x32_bf16 v[12:15], v[160:163], v[214:217], v[12:15]
	v_mfma_f32_16x16x32_bf16 v[64:67], v[156:159], v[192:195], v[64:67]
	v_mfma_f32_16x16x32_bf16 v[60:63], v[168:171], v[192:195], v[60:63]
	v_mfma_f32_16x16x32_bf16 v[48:51], v[156:159], v[200:203], v[48:51]
	v_mfma_f32_16x16x32_bf16 v[44:47], v[168:171], v[200:203], v[44:47]
	v_mfma_f32_16x16x32_bf16 v[32:35], v[156:159], v[210:213], v[32:35]
	v_mfma_f32_16x16x32_bf16 v[28:31], v[168:171], v[210:213], v[28:31]
	v_mfma_f32_16x16x32_bf16 v[16:19], v[156:159], v[218:221], v[16:19]
	v_mfma_f32_16x16x32_bf16 v[12:15], v[168:171], v[218:221], v[12:15]
	v_mfma_f32_16x16x32_bf16 v[56:59], v[172:175], v[188:191], v[56:59]
	v_mfma_f32_16x16x32_bf16 v[52:55], v[180:183], v[188:191], v[52:55]
	v_mfma_f32_16x16x32_bf16 v[40:43], v[172:175], v[196:199], v[40:43]
	v_mfma_f32_16x16x32_bf16 v[36:39], v[180:183], v[196:199], v[36:39]
	v_mfma_f32_16x16x32_bf16 v[24:27], v[172:175], v[204:207], v[24:27]
	v_mfma_f32_16x16x32_bf16 v[20:23], v[180:183], v[204:207], v[20:23]
	v_mfma_f32_16x16x32_bf16 v[8:11], v[172:175], v[214:217], v[8:11]
	v_mfma_f32_16x16x32_bf16 v[4:7], v[180:183], v[214:217], v[4:7]
	v_mfma_f32_16x16x32_bf16 v[56:59], v[176:179], v[192:195], v[56:59]
	v_mfma_f32_16x16x32_bf16 v[52:55], v[184:187], v[192:195], v[52:55]
	v_mfma_f32_16x16x32_bf16 v[40:43], v[176:179], v[200:203], v[40:43]
	v_mfma_f32_16x16x32_bf16 v[36:39], v[184:187], v[200:203], v[36:39]
	v_mfma_f32_16x16x32_bf16 v[24:27], v[176:179], v[210:213], v[24:27]
	v_mfma_f32_16x16x32_bf16 v[20:23], v[184:187], v[210:213], v[20:23]
	v_mfma_f32_16x16x32_bf16 v[8:11], v[176:179], v[218:221], v[8:11]
	v_mfma_f32_16x16x32_bf16 v[4:7], v[184:187], v[218:221], v[4:7]
	s_barrier
	s_setprio 0
	s_add_i32 s9, 0, 0x18000
	v_add_u32_e32 v2, s9, v147
	s_add_i32 s29, 0, 0x1c000
	ds_read_b128 v[152:155], v2
	ds_read_b128 v[156:159], v2 offset:1024
	ds_read_b128 v[160:163], v2 offset:2048
	ds_read_b128 v[168:171], v2 offset:3072
	v_add_u32_e32 v2, s29, v147
	ds_read_b128 v[172:175], v2
	ds_read_b128 v[176:179], v2 offset:1024
	ds_read_b128 v[180:183], v2 offset:2048
	ds_read_b128 v[184:187], v2 offset:3072
	s_add_u32 s22, s22, s16
	s_addc_u32 s23, s23, 0
	s_mov_b32 m0, s49
	ds_read_b128 v[188:191], v150 offset:32768
	ds_read_b128 v[192:195], v150 offset:33792
	ds_read_b128 v[196:199], v150 offset:34816
	ds_read_b128 v[200:203], v150 offset:35840
	ds_read_b128 v[204:207], v150 offset:36864
	ds_read_b128 v[210:213], v150 offset:37888
	ds_read_b128 v[214:217], v150 offset:38912
	ds_read_b128 v[218:221], v150 offset:39936
	global_load_lds_dwordx4 v138, s[22:23]
	s_mov_b32 m0, s50
	s_nop 0
	global_load_lds_dwordx4 v134, s[22:23]
	s_waitcnt vmcnt(8)
	s_waitcnt lgkmcnt(0)
	s_setprio 1
	s_barrier
	v_mfma_f32_16x16x32_bf16 v[128:131], v[152:155], v[188:191], v[128:131]
	v_mfma_f32_16x16x32_bf16 v[124:127], v[160:163], v[188:191], v[124:127]
	v_mfma_f32_16x16x32_bf16 v[112:115], v[152:155], v[196:199], v[112:115]
	v_mfma_f32_16x16x32_bf16 v[108:111], v[160:163], v[196:199], v[108:111]
	v_mfma_f32_16x16x32_bf16 v[96:99], v[152:155], v[204:207], v[96:99]
	v_mfma_f32_16x16x32_bf16 v[92:95], v[160:163], v[204:207], v[92:95]
	v_mfma_f32_16x16x32_bf16 v[80:83], v[152:155], v[214:217], v[80:83]
	v_mfma_f32_16x16x32_bf16 v[76:79], v[160:163], v[214:217], v[76:79]
	v_mfma_f32_16x16x32_bf16 v[128:131], v[156:159], v[192:195], v[128:131]
	v_mfma_f32_16x16x32_bf16 v[124:127], v[168:171], v[192:195], v[124:127]
	v_mfma_f32_16x16x32_bf16 v[112:115], v[156:159], v[200:203], v[112:115]
	v_mfma_f32_16x16x32_bf16 v[108:111], v[168:171], v[200:203], v[108:111]
	v_mfma_f32_16x16x32_bf16 v[96:99], v[156:159], v[210:213], v[96:99]
	v_mfma_f32_16x16x32_bf16 v[92:95], v[168:171], v[210:213], v[92:95]
	v_mfma_f32_16x16x32_bf16 v[80:83], v[156:159], v[218:221], v[80:83]
	v_mfma_f32_16x16x32_bf16 v[76:79], v[168:171], v[218:221], v[76:79]
	v_mfma_f32_16x16x32_bf16 v[120:123], v[172:175], v[188:191], v[120:123]
	v_mfma_f32_16x16x32_bf16 v[116:119], v[180:183], v[188:191], v[116:119]
	v_mfma_f32_16x16x32_bf16 v[104:107], v[172:175], v[196:199], v[104:107]
	v_mfma_f32_16x16x32_bf16 v[100:103], v[180:183], v[196:199], v[100:103]
	v_mfma_f32_16x16x32_bf16 v[88:91], v[172:175], v[204:207], v[88:91]
	v_mfma_f32_16x16x32_bf16 v[84:87], v[180:183], v[204:207], v[84:87]
	v_mfma_f32_16x16x32_bf16 v[72:75], v[172:175], v[214:217], v[72:75]
	v_mfma_f32_16x16x32_bf16 v[68:71], v[180:183], v[214:217], v[68:71]
	v_mfma_f32_16x16x32_bf16 v[120:123], v[176:179], v[192:195], v[120:123]
	v_mfma_f32_16x16x32_bf16 v[116:119], v[184:187], v[192:195], v[116:119]
	v_mfma_f32_16x16x32_bf16 v[104:107], v[176:179], v[200:203], v[104:107]
	v_mfma_f32_16x16x32_bf16 v[100:103], v[184:187], v[200:203], v[100:103]
	v_mfma_f32_16x16x32_bf16 v[88:91], v[176:179], v[210:213], v[88:91]
	v_mfma_f32_16x16x32_bf16 v[84:87], v[184:187], v[210:213], v[84:87]
	v_mfma_f32_16x16x32_bf16 v[72:75], v[176:179], v[218:221], v[72:75]
	v_mfma_f32_16x16x32_bf16 v[68:71], v[184:187], v[218:221], v[68:71]
	s_barrier
	s_setprio 0
	s_add_i32 s9, s9, s26
	s_mov_b32 m0, s9
	ds_read_b128 v[188:191], v150 offset:49152
	ds_read_b128 v[192:195], v150 offset:50176
	ds_read_b128 v[196:199], v150 offset:51200
	ds_read_b128 v[200:203], v150 offset:52224
	ds_read_b128 v[204:207], v150 offset:53248
	ds_read_b128 v[210:213], v150 offset:54272
	ds_read_b128 v[214:217], v150 offset:55296
	ds_read_b128 v[218:221], v150 offset:56320
	s_sub_u32 s34, s34, s16
	s_subb_u32 s35, s35, 0
	s_add_u32 s34, s34, 0x80
	s_addc_u32 s35, s35, 0
	global_load_lds_dwordx4 v136, s[34:35]
	s_add_i32 m0, s9, 0x2000
	s_add_i32 s9, s29, s26
	global_load_lds_dwordx4 v132, s[34:35]
	s_mov_b32 m0, s9
	s_nop 0
	s_add_u32 s34, s34, s16
	s_addc_u32 s35, s35, 0
	global_load_lds_dwordx4 v136, s[34:35]
	s_add_i32 m0, s9, 0x2000
	s_nop 0
	global_load_lds_dwordx4 v132, s[34:35]
	s_mov_b32 m0, s53
	s_nop 0
	s_sub_u32 s22, s22, s16
	s_subb_u32 s23, s23, 0
	s_add_u32 s22, s22, s100
	s_addc_u32 s23, s23, 0
	global_load_lds_dwordx4 v138, s[22:23]
	s_mov_b32 m0, s54
	s_nop 0
	global_load_lds_dwordx4 v134, s[22:23]
	s_waitcnt vmcnt(8)
	s_waitcnt lgkmcnt(0)
	s_setprio 1
	s_barrier
	v_mfma_f32_16x16x32_bf16 v[64:67], v[152:155], v[188:191], v[64:67]
	v_mfma_f32_16x16x32_bf16 v[60:63], v[160:163], v[188:191], v[60:63]
	v_mfma_f32_16x16x32_bf16 v[48:51], v[152:155], v[196:199], v[48:51]
	v_mfma_f32_16x16x32_bf16 v[44:47], v[160:163], v[196:199], v[44:47]
	v_mfma_f32_16x16x32_bf16 v[32:35], v[152:155], v[204:207], v[32:35]
	v_mfma_f32_16x16x32_bf16 v[28:31], v[160:163], v[204:207], v[28:31]
	v_mfma_f32_16x16x32_bf16 v[16:19], v[152:155], v[214:217], v[16:19]
	v_mfma_f32_16x16x32_bf16 v[12:15], v[160:163], v[214:217], v[12:15]
	v_mfma_f32_16x16x32_bf16 v[64:67], v[156:159], v[192:195], v[64:67]
	v_mfma_f32_16x16x32_bf16 v[60:63], v[168:171], v[192:195], v[60:63]
	v_mfma_f32_16x16x32_bf16 v[48:51], v[156:159], v[200:203], v[48:51]
	v_mfma_f32_16x16x32_bf16 v[44:47], v[168:171], v[200:203], v[44:47]
	v_mfma_f32_16x16x32_bf16 v[32:35], v[156:159], v[210:213], v[32:35]
	v_mfma_f32_16x16x32_bf16 v[28:31], v[168:171], v[210:213], v[28:31]
	v_mfma_f32_16x16x32_bf16 v[16:19], v[156:159], v[218:221], v[16:19]
	v_mfma_f32_16x16x32_bf16 v[12:15], v[168:171], v[218:221], v[12:15]
	v_mfma_f32_16x16x32_bf16 v[56:59], v[172:175], v[188:191], v[56:59]
	v_mfma_f32_16x16x32_bf16 v[52:55], v[180:183], v[188:191], v[52:55]
	v_mfma_f32_16x16x32_bf16 v[40:43], v[172:175], v[196:199], v[40:43]
	v_mfma_f32_16x16x32_bf16 v[36:39], v[180:183], v[196:199], v[36:39]
	v_mfma_f32_16x16x32_bf16 v[24:27], v[172:175], v[204:207], v[24:27]
	v_mfma_f32_16x16x32_bf16 v[20:23], v[180:183], v[204:207], v[20:23]
	v_mfma_f32_16x16x32_bf16 v[8:11], v[172:175], v[214:217], v[8:11]
	v_mfma_f32_16x16x32_bf16 v[4:7], v[180:183], v[214:217], v[4:7]
	v_mfma_f32_16x16x32_bf16 v[56:59], v[176:179], v[192:195], v[56:59]
	v_mfma_f32_16x16x32_bf16 v[52:55], v[184:187], v[192:195], v[52:55]
	v_mfma_f32_16x16x32_bf16 v[40:43], v[176:179], v[200:203], v[40:43]
	v_mfma_f32_16x16x32_bf16 v[36:39], v[184:187], v[200:203], v[36:39]
	s_cmp_ge_u32 s28, s51
	v_mfma_f32_16x16x32_bf16 v[24:27], v[176:179], v[210:213], v[24:27]
	v_mfma_f32_16x16x32_bf16 v[20:23], v[184:187], v[210:213], v[20:23]
	v_mfma_f32_16x16x32_bf16 v[8:11], v[176:179], v[218:221], v[8:11]
	v_mfma_f32_16x16x32_bf16 v[4:7], v[184:187], v[218:221], v[4:7]
	s_cbranch_scc1 .Lexit_832
	s_barrier
	s_setprio 0
	s_add_u32 s2, s2, s98
	s_addc_u32 s3, s3, 0
	s_add_u32 s7, s7, 0x100
	s_addc_u32 s8, s8, 0
	s_cmp_ge_u32 s28, s51
	s_mov_b32 s9, s28
	s_cbranch_scc0 .LBB0_832
.Lexit_832:
	s_setprio 0
	s_add_u32 s2, s2, s98
	s_addc_u32 s3, s3, 0
	s_add_u32 s7, s7, 0x100
	s_addc_u32 s8, s8, 0
	s_mov_b32 s9, s28
